# P4/P6: the first two residual-tile loads of the epilogue issued at unit start into spare registers
# speedup vs baseline: 1.0005x; 1.0005x over previous
.Lnr_p4:
	s_lshl_b32 s98, s5, 16
	s_lshl_b32 s99, s4, 20
	s_add_i32 s98, s99, s98
	s_or_b32 s100, s98, 0x8000
	s_add_u32 s98, s46, s98
	s_addc_u32 s99, s47, 0
	v_lshl_add_u64 v[92:93], s[98:99], 0, v[80:81]
	global_load_dwordx4 v[84:87], v[92:93], off
	s_add_u32 s98, s46, s100
	s_addc_u32 s99, s47, 0
	v_lshl_add_u64 v[92:93], s[98:99], 0, v[80:81]
	global_load_dwordx4 v[88:91], v[92:93], off
	s_add_i32 s90, s90, 1
	v_readlane_b32 s6, v250, 2
	s_lshl_b32 s7, s90, 8
	s_add_i32 s7, s7, s6
	s_cmp_lt_u32 s7, 0x200
	s_cselect_b64 s[40:41], -1, 0
	s_lshl_b32 s7, s90, 5
	s_lshr_b32 s10, s6, 3
	s_add_i32 s7, s7, s10
	s_and_b32 s6, s6, 7
	s_lshl_b32 s6, s6, 3
	s_cmp_ge_u32 s7, 0x20
	s_cselect_b32 s10, 0x20, 0
	s_cselect_b32 s92, 0, 4
	s_sub_i32 s7, s7, s10
	s_add_i32 s92, s92, s6
	s_and_b32 s6, s7, 3
	s_add_i32 s92, s92, s6
	s_lshr_b32 s93, s7, 2

.LBB0_694:
	s_lshl_b32 s5, s5, 16
	s_lshl_b32 s6, s4, 20
	s_add_i32 s5, s6, s5
	s_add_u32 s74, s46, s5
	s_addc_u32 s75, s47, 0
	s_mov_b64 s[6:7], s[74:75]
	s_nop 0
	v_lshl_add_u64 v[128:129], s[6:7], 0, v[80:81]
	s_or_b32 s6, s5, 0x8000
	s_add_u32 s72, s46, s6
	s_addc_u32 s73, s47, 0
	s_mov_b64 s[6:7], s[72:73]
	s_add_u32 s70, s74, 0x800
	v_mov_b32_e32 v224, v84
	v_mov_b32_e32 v225, v85
	v_mov_b32_e32 v226, v86
	v_mov_b32_e32 v227, v87
	s_addc_u32 s71, s75, 0
	v_lshl_add_u64 v[128:129], s[6:7], 0, v[80:81]
	s_mov_b64 s[6:7], s[70:71]
	v_mov_b32_e32 v228, v88
	v_mov_b32_e32 v229, v89
	v_mov_b32_e32 v230, v90
	v_mov_b32_e32 v231, v91
	s_and_b64 vcc, exec, s[2:3]
	s_cbranch_vccz .Lab_p4
	s_barrier

.Lnr_p6:
	s_lshl_b32 s98, s5, 16
	s_lshl_b32 s99, s4, 20
	s_add_i32 s98, s99, s98
	s_or_b32 s100, s98, 0x8000
	s_add_u32 s98, s46, s98
	s_addc_u32 s99, s47, 0
	v_lshl_add_u64 v[92:93], s[98:99], 0, v[80:81]
	global_load_dwordx4 v[84:87], v[92:93], off
	s_add_u32 s98, s46, s100
	s_addc_u32 s99, s47, 0
	v_lshl_add_u64 v[92:93], s[98:99], 0, v[80:81]
	global_load_dwordx4 v[88:91], v[92:93], off
	s_add_i32 s88, s88, 1
	v_readlane_b32 s6, v250, 2
	s_lshl_b32 s7, s88, 8
	s_add_i32 s7, s7, s6
	s_cmp_lt_u32 s7, 0x200
	s_cselect_b64 s[38:39], -1, 0
	s_lshl_b32 s7, s88, 5
	s_lshr_b32 s10, s6, 3
	s_add_i32 s7, s7, s10
	s_and_b32 s6, s6, 7
	s_lshl_b32 s6, s6, 3
	s_cmp_ge_u32 s7, 0x20
	s_cselect_b32 s10, 0x20, 0
	s_cselect_b32 s90, 0, 4
	s_sub_i32 s7, s7, s10
	s_add_i32 s90, s90, s6
	s_and_b32 s6, s7, 3
	s_add_i32 s90, s90, s6
	s_lshr_b32 s91, s7, 2

.LBB0_888:
	s_lshl_b32 s5, s5, 16
	s_lshl_b32 s6, s4, 20
	s_add_i32 s5, s6, s5
	s_add_u32 s72, s46, s5
	s_addc_u32 s73, s47, 0
	s_mov_b64 s[6:7], s[72:73]
	s_nop 0
	v_lshl_add_u64 v[128:129], s[6:7], 0, v[80:81]
	s_or_b32 s6, s5, 0x8000
	s_add_u32 s70, s46, s6
	s_addc_u32 s71, s47, 0
	s_mov_b64 s[6:7], s[70:71]
	s_add_u32 s68, s72, 0x800
	v_mov_b32_e32 v224, v84
	v_mov_b32_e32 v225, v85
	v_mov_b32_e32 v226, v86
	v_mov_b32_e32 v227, v87
	s_addc_u32 s69, s73, 0
	v_lshl_add_u64 v[128:129], s[6:7], 0, v[80:81]
	s_mov_b64 s[6:7], s[68:69]
	v_mov_b32_e32 v228, v88
	v_mov_b32_e32 v229, v89
	v_mov_b32_e32 v230, v90
	v_mov_b32_e32 v231, v91
	s_and_b64 vcc, exec, s[2:3]
	s_cbranch_vccz .Lab_p6
	s_barrier
